# counted-wait row-statistic prefetch (loads in last K iteration, vmcnt(16) at epilogue head) also applied to the mixer in-projection GEMM epilogue (phase 3)
# speedup vs baseline: 1.0008x; 1.0008x over previous
; template <class Epi, class Sched, bool ALIGN_EPI = false, bool SP2 = false>
; __device__ __forceinline__ void gemm_phase(PG8_LAS unsigned char* lds, const Gemm g, const Sched& S, const Epi& E, int tid_in) {
;     ...
;         const bool has_next = S.next(ui + 1, nxt);
;         const char* nA = has_next ? (const char*)g.A + (size_t)nxt.pm * tstep : cA; const char* nB = has_next ? (const char*)g.Bt + (size_t)nxt.pn * tstep : cB;
;         constexpr int NHK = Epi::HAS_MID ? 2 : 1;
; #pragma unroll
;         for (int hk = 0; hk < NHK; ++hk) {
;         if constexpr (Epi::HAS_MID) { if (hk == 1) E.mid(acc, cur, wr, fr); }
;         const int t_beg = hk * (nt / NHK), t_end = (hk + 1) * (nt / NHK);
;         for (int t = t_beg; t < t_end; t += 2) {
;             const bool last = (t == nt - 2);
;             const char* a1 = cA + (size_t)(t + 1) * kstep;
;             const char* a2 = last ? nA : cA + (size_t)(t + 2) * kstep; const char* b2 = last ? nB : cB + (size_t)(t + 2) * kstep;
;             const char* a3 = a2 + kstep; const char* b3 = b2 + kstep;
;             if (last && has_next) S.a_ready(nxt);
;             if constexpr (SP2) {
;             PG8_LDB(B0, 0, 0); PG8_LDB(B1, 0, 1); PG8_SCHED; PG8_LDA(At, 0, 0); PG8_STAGE(PG8_SA(1, 1), a1 + hstep, voffA);
;             PG8_WAIT_V(8); PG8_WAIT_L(0); PG8_BAR; PG8_MMA(0, 0, At, B0); PG8_MMA(0, 1, At, B1); PG8_BAR; PG8_SCHED;
;             PG8_LDA(At, 0, 1); PG8_STAGE(PG8_SB(0, 0), b2, voffB); PG8_STAGE(PG8_SB(0, 1), b2 + hstep, voffB); PG8_STAGE(PG8_SA(0, 0), a2, voffA);
;             PG8_WAIT_V(8); PG8_WAIT_L(0); PG8_BAR; PG8_MMA(1, 0, At, B0); PG8_MMA(1, 1, At, B1); PG8_BAR; PG8_SCHED;
;             PG8_LDB(B0, 1, 0); PG8_LDB(B1, 1, 1); PG8_SCHED; PG8_LDA(At, 1, 0); PG8_STAGE(PG8_SA(0, 1), a2 + hstep, voffA);
;             PG8_WAIT_V(8); PG8_WAIT_L(0); PG8_BAR; PG8_MMA(0, 0, At, B0); PG8_MMA(0, 1, At, B1); PG8_BAR; PG8_SCHED;
;             PG8_LDA(At, 1, 1); PG8_STAGE(PG8_SB(1, 0), b3, voffB); PG8_STAGE(PG8_SB(1, 1), b3 + hstep, voffB); PG8_STAGE(PG8_SA(1, 0), a3, voffA);
;             PG8_WAIT_V(8); PG8_WAIT_L(0); PG8_BAR; PG8_MMA(1, 0, At, B0); PG8_MMA(1, 1, At, B1); PG8_BAR; PG8_SCHED;
;             } else {
;             PG8_LDB(B0, 0, 0); PG8_SCHED; PG8_LDA(At, 0, 0); PG8_STAGE(PG8_SA(1, 1), a1 + hstep, voffA);
;             PG8_WAIT_L(8); PG8_BAR; PG8_WAIT_L(0); PG8_MMA(0, 0, At, B0); PG8_BAR; PG8_SCHED;
.LBB0_84:
	s_ashr_i32 s37, s36, 31
	s_lshl_b64 s[10:11], s[36:37], 20
	s_add_u32 s42, s20, s10
	s_addc_u32 s43, s21, s11
	s_and_b64 s[10:11], s[38:39], exec
	s_cselect_b32 s3, s43, s53
	s_cselect_b32 s10, s42, s52
	s_ashr_i32 s35, s34, 31
	s_lshl_b64 s[14:15], s[34:35], 20
	s_add_u32 s44, s8, s14
	s_addc_u32 s45, s9, s15
	s_and_b64 s[14:15], s[38:39], exec
	s_cselect_b32 s11, s45, s51
	s_cselect_b32 s35, s44, s50
	s_add_u32 s37, s50, 0x100
	s_addc_u32 s41, s51, 0
	s_add_u32 s50, s52, 0x80080
	v_mov_b32_e32 v0, 0
	s_addc_u32 s51, s53, 0
	s_mov_b32 s97, -2
	v_mov_b32_e32 v1, v0
	v_mov_b32_e32 v2, v0
	v_mov_b32_e32 v3, v0
	v_mov_b32_e32 v4, v0
	v_mov_b32_e32 v5, v0
	v_mov_b32_e32 v6, v0
	v_mov_b32_e32 v7, v0
	v_mov_b32_e32 v16, v0
	v_mov_b32_e32 v17, v0
	v_mov_b32_e32 v18, v0
	v_mov_b32_e32 v19, v0
	v_mov_b32_e32 v20, v0
	v_mov_b32_e32 v21, v0
	v_mov_b32_e32 v22, v0
	v_mov_b32_e32 v23, v0
	v_mov_b32_e32 v32, v0
	v_mov_b32_e32 v33, v0
	v_mov_b32_e32 v34, v0
	v_mov_b32_e32 v35, v0
	v_mov_b32_e32 v36, v0
	v_mov_b32_e32 v37, v0
	v_mov_b32_e32 v38, v0
	v_mov_b32_e32 v39, v0
	v_mov_b32_e32 v48, v0
	v_mov_b32_e32 v49, v0
	v_mov_b32_e32 v50, v0
	v_mov_b32_e32 v51, v0
	v_mov_b32_e32 v52, v0
	v_mov_b32_e32 v53, v0
	v_mov_b32_e32 v54, v0
	v_mov_b32_e32 v55, v0
	v_mov_b32_e32 v8, v0
	v_mov_b32_e32 v9, v0
	v_mov_b32_e32 v10, v0
	v_mov_b32_e32 v11, v0
	v_mov_b32_e32 v12, v0
	v_mov_b32_e32 v13, v0
	v_mov_b32_e32 v14, v0
	v_mov_b32_e32 v15, v0
	v_mov_b32_e32 v24, v0
	v_mov_b32_e32 v25, v0
	v_mov_b32_e32 v26, v0
	v_mov_b32_e32 v27, v0
	v_mov_b32_e32 v28, v0
	v_mov_b32_e32 v29, v0
	v_mov_b32_e32 v30, v0
	v_mov_b32_e32 v31, v0
	v_mov_b32_e32 v40, v0
	v_mov_b32_e32 v41, v0
	v_mov_b32_e32 v42, v0
	v_mov_b32_e32 v43, v0
	v_mov_b32_e32 v44, v0
	v_mov_b32_e32 v45, v0
	v_mov_b32_e32 v46, v0
	v_mov_b32_e32 v47, v0
	v_mov_b32_e32 v56, v0
	v_mov_b32_e32 v57, v0
	v_mov_b32_e32 v58, v0
	v_mov_b32_e32 v59, v0
	v_mov_b32_e32 v60, v0
	v_mov_b32_e32 v61, v0
	v_mov_b32_e32 v62, v0
	v_mov_b32_e32 v63, v0
	v_mov_b32_e32 v64, v0
	v_mov_b32_e32 v65, v0
	v_mov_b32_e32 v66, v0
	v_mov_b32_e32 v67, v0
	v_mov_b32_e32 v68, v0
	v_mov_b32_e32 v69, v0
	v_mov_b32_e32 v70, v0
	v_mov_b32_e32 v71, v0
	v_mov_b32_e32 v80, v0
	v_mov_b32_e32 v81, v0
	v_mov_b32_e32 v82, v0
	v_mov_b32_e32 v83, v0
	v_mov_b32_e32 v84, v0
	v_mov_b32_e32 v85, v0
	v_mov_b32_e32 v86, v0
	v_mov_b32_e32 v87, v0
	v_mov_b32_e32 v96, v0
	v_mov_b32_e32 v97, v0
	v_mov_b32_e32 v98, v0
	v_mov_b32_e32 v99, v0
	v_mov_b32_e32 v100, v0
	v_mov_b32_e32 v101, v0
	v_mov_b32_e32 v102, v0
	v_mov_b32_e32 v103, v0
	v_mov_b32_e32 v112, v0
	v_mov_b32_e32 v113, v0
	v_mov_b32_e32 v114, v0
	v_mov_b32_e32 v115, v0
	v_mov_b32_e32 v116, v0
	v_mov_b32_e32 v117, v0
	v_mov_b32_e32 v118, v0
	v_mov_b32_e32 v119, v0
	v_mov_b32_e32 v72, v0
	v_mov_b32_e32 v73, v0
	v_mov_b32_e32 v74, v0
	v_mov_b32_e32 v75, v0
	v_mov_b32_e32 v76, v0
	v_mov_b32_e32 v77, v0
	v_mov_b32_e32 v78, v0
	v_mov_b32_e32 v79, v0
	v_mov_b32_e32 v88, v0
	v_mov_b32_e32 v89, v0
	v_mov_b32_e32 v90, v0
	v_mov_b32_e32 v91, v0
	v_mov_b32_e32 v92, v0
	v_mov_b32_e32 v93, v0
	v_mov_b32_e32 v94, v0
	v_mov_b32_e32 v95, v0
	v_mov_b32_e32 v104, v0
	v_mov_b32_e32 v105, v0
	v_mov_b32_e32 v106, v0
	v_mov_b32_e32 v107, v0
	v_mov_b32_e32 v108, v0
	v_mov_b32_e32 v109, v0
	v_mov_b32_e32 v110, v0
	v_mov_b32_e32 v111, v0
	v_mov_b32_e32 v120, v0
	v_mov_b32_e32 v121, v0
	v_mov_b32_e32 v122, v0
	v_mov_b32_e32 v123, v0
	v_mov_b32_e32 v124, v0
	v_mov_b32_e32 v125, v0
	v_mov_b32_e32 v126, v0
	v_mov_b32_e32 v127, v0
	v_lshl_add_u32 v252, s40, 8, v137
	v_ashrrev_i32_e32 v253, 31, v252
	v_lshl_add_u64 v[252:253], v[252:253], 2, s[18:19]
.LBB0_85:
	s_add_u32 s14, s50, 0xfff80080
	s_addc_u32 s15, s51, -1
	s_add_i32 vcc_lo, 0, 0x10000
	s_cmp_eq_u32 s97, 28
	s_cselect_b32 s15, s3, s15
	s_cselect_b32 s14, s10, s14
	s_cselect_b32 s53, s11, s41
	s_cselect_b32 s52, s35, s37
	s_cbranch_scc0 .Lss2_skip
	global_load_dword v228, v[252:253], off
	global_load_dword v229, v[252:253], off offset:64
	global_load_dword v230, v[252:253], off offset:128
	global_load_dword v231, v[252:253], off offset:192
	global_load_dword v232, v[252:253], off offset:512
	global_load_dword v233, v[252:253], off offset:576
	global_load_dword v234, v[252:253], off offset:640
	global_load_dword v244, v[252:253], off offset:704
; #define PG8_STAGE(bufoff, gbase, voff) do { _Pragma("unroll") for (int _i = 0; _i < 2; ++_i) \
;         __builtin_amdgcn_global_load_lds((const unsigned*)((const char*)(gbase) + (voff)[_i]), (PG8_LAS unsigned*)(lds + (bufoff) + ldsw + _i * 8192), 16, 0, 0); } while (0)
; #define PG8_LDA(dst, b, h) do { _Pragma("unroll") for (int m = 0; m < 4; ++m) _Pragma("unroll") for (int k = 0; k < 2; ++k) dst[m][k] = *(const PG8_LAS bf16x8*)(lds + PG8_SA(b, h) + aoff + m * 2048 + k * 1024); } while (0)
; #define PG8_LDB(dst, b, h) do { _Pragma("unroll") for (int n = 0; n < 2; ++n) _Pragma("unroll") for (int k = 0; k < 2; ++k) dst[n][k] = *(const PG8_LAS bf16x8*)(lds + PG8_SB(b, h) + boff + n * 2048 + k * 1024); } while (0)
; #define PG8_MMA(ai, bj, At, Bt) do { __builtin_amdgcn_s_setprio(1); _Pragma("unroll") for (int m = 0; m < 4; ++m) _Pragma("unroll") for (int n = 0; n < 2; ++n) _Pragma("unroll") for (int k = 0; k < 2; ++k) \
;         acc[ai][bj][m][n] = __builtin_amdgcn_mfma_f32_16x16x32_bf16(Bt[n][k], At[m][k], acc[ai][bj][m][n], 0, 0, 0); __builtin_amdgcn_s_setprio(0); } while (0)
; #define PG8_WAIT_V(n) asm volatile("s_waitcnt vmcnt(" #n ")" ::: "memory")
; #define PG8_WAIT_L(n) asm volatile("s_waitcnt lgkmcnt(" #n ")" ::: "memory")
; #define PG8_BAR __builtin_amdgcn_s_barrier()
; #define PG8_SCHED __builtin_amdgcn_sched_barrier(0)
; template <class Epi, class Sched, bool ALIGN_EPI = false, bool SP2 = false>
; __device__ __forceinline__ void gemm_phase(PG8_LAS unsigned char* lds, const Gemm g, const Sched& S, const Epi& E, int tid_in) {
;     ...
;             if constexpr (SP2) {
;             PG8_LDB(B0, 0, 0); PG8_LDB(B1, 0, 1); PG8_SCHED; PG8_LDA(At, 0, 0); PG8_STAGE(PG8_SA(1, 1), a1 + hstep, voffA);
;             PG8_WAIT_V(8); PG8_WAIT_L(0); PG8_BAR; PG8_MMA(0, 0, At, B0); PG8_MMA(0, 1, At, B1); PG8_BAR; PG8_SCHED;
;             PG8_LDA(At, 0, 1); PG8_STAGE(PG8_SB(0, 0), b2, voffB); PG8_STAGE(PG8_SB(0, 1), b2 + hstep, voffB); PG8_STAGE(PG8_SA(0, 0), a2, voffA);
;             PG8_WAIT_V(8); PG8_WAIT_L(0); PG8_BAR; PG8_MMA(1, 0, At, B0); PG8_MMA(1, 1, At, B1); PG8_BAR; PG8_SCHED;
.Lss2_skip:
	s_add_i32 s12, 0, 0x14000
	v_add_u32_e32 v156, vcc_lo, v146
	v_add_u32_e32 v172, s12, v146
	ds_read_b128 v[142:145], v156
	ds_read_b128 v[148:151], v156 offset:1024
	ds_read_b128 v[152:155], v156 offset:2048
	ds_read_b128 v[156:159], v156 offset:3072
	ds_read_b128 v[160:163], v172
	ds_read_b128 v[164:167], v172 offset:1024
	ds_read_b128 v[168:171], v172 offset:2048
	ds_read_b128 v[172:175], v172 offset:3072
	v_lshl_add_u64 v[202:203], s[50:51], 0, v[140:141]
	s_add_i32 m0, s46, 0xc000
	ds_read_b128 v[176:179], v147
	ds_read_b128 v[180:183], v147 offset:1024
	ds_read_b128 v[184:187], v147 offset:2048
	ds_read_b128 v[188:191], v147 offset:3072
	ds_read_b128 v[194:197], v147 offset:4096
	ds_read_b128 v[198:201], v147 offset:5120
	ds_read_b128 v[212:215], v147 offset:6144
	ds_read_b128 v[216:219], v147 offset:7168
	global_load_lds_dwordx4 v[202:203], off
	v_lshl_add_u64 v[202:203], s[50:51], 0, v[138:139]
	s_add_i32 m0, s46, 0xe000
	s_nop 0
	global_load_lds_dwordx4 v[202:203], off
	s_waitcnt vmcnt(8)
	s_waitcnt lgkmcnt(0)
	s_barrier
	s_setprio 1
	s_waitcnt lgkmcnt(0)
	v_mfma_f32_16x16x32_bf16 v[124:127], v[142:145], v[176:179], v[124:127]
	v_mfma_f32_16x16x32_bf16 v[120:123], v[152:155], v[176:179], v[120:123]
	v_mfma_f32_16x16x32_bf16 v[108:111], v[142:145], v[184:187], v[108:111]
	v_mfma_f32_16x16x32_bf16 v[104:107], v[152:155], v[184:187], v[104:107]
	v_mfma_f32_16x16x32_bf16 v[92:95], v[142:145], v[194:197], v[92:95]
	v_mfma_f32_16x16x32_bf16 v[88:91], v[152:155], v[194:197], v[88:91]
	v_mfma_f32_16x16x32_bf16 v[76:79], v[142:145], v[212:215], v[76:79]
	v_mfma_f32_16x16x32_bf16 v[72:75], v[152:155], v[212:215], v[72:75]
	v_mfma_f32_16x16x32_bf16 v[124:127], v[148:151], v[180:183], v[124:127]
	v_mfma_f32_16x16x32_bf16 v[120:123], v[156:159], v[180:183], v[120:123]
	v_mfma_f32_16x16x32_bf16 v[108:111], v[148:151], v[188:191], v[108:111]
	v_mfma_f32_16x16x32_bf16 v[104:107], v[156:159], v[188:191], v[104:107]
	v_mfma_f32_16x16x32_bf16 v[92:95], v[148:151], v[198:201], v[92:95]
	v_mfma_f32_16x16x32_bf16 v[88:91], v[156:159], v[198:201], v[88:91]
	v_mfma_f32_16x16x32_bf16 v[76:79], v[148:151], v[216:219], v[76:79]
	v_mfma_f32_16x16x32_bf16 v[72:75], v[156:159], v[216:219], v[72:75]
	s_setprio 0
	s_setprio 1
	v_mfma_f32_16x16x32_bf16 v[116:119], v[160:163], v[176:179], v[116:119]
	v_mfma_f32_16x16x32_bf16 v[112:115], v[168:171], v[176:179], v[112:115]
	v_mfma_f32_16x16x32_bf16 v[100:103], v[160:163], v[184:187], v[100:103]
	v_mfma_f32_16x16x32_bf16 v[96:99], v[168:171], v[184:187], v[96:99]
	v_mfma_f32_16x16x32_bf16 v[84:87], v[160:163], v[194:197], v[84:87]
	v_mfma_f32_16x16x32_bf16 v[80:83], v[168:171], v[194:197], v[80:83]
	v_mfma_f32_16x16x32_bf16 v[68:71], v[160:163], v[212:215], v[68:71]
	v_mfma_f32_16x16x32_bf16 v[64:67], v[168:171], v[212:215], v[64:67]
	v_mfma_f32_16x16x32_bf16 v[116:119], v[164:167], v[180:183], v[116:119]
	v_mfma_f32_16x16x32_bf16 v[112:115], v[172:175], v[180:183], v[112:115]
	v_mfma_f32_16x16x32_bf16 v[100:103], v[164:167], v[188:191], v[100:103]
	v_mfma_f32_16x16x32_bf16 v[96:99], v[172:175], v[188:191], v[96:99]
	v_mfma_f32_16x16x32_bf16 v[84:87], v[164:167], v[198:201], v[84:87]
	v_mfma_f32_16x16x32_bf16 v[80:83], v[172:175], v[198:201], v[80:83]
	v_mfma_f32_16x16x32_bf16 v[68:71], v[164:167], v[216:219], v[68:71]
	v_mfma_f32_16x16x32_bf16 v[64:67], v[172:175], v[216:219], v[64:67]
	s_setprio 0
	s_barrier
	s_add_i32 s13, vcc_lo, s23
	v_lshl_add_u64 v[202:203], s[52:53], 0, v[130:131]
	s_mov_b32 m0, s13
	ds_read_b128 v[176:179], v147 offset:16384
	ds_read_b128 v[180:183], v147 offset:17408
	ds_read_b128 v[184:187], v147 offset:18432
	ds_read_b128 v[188:191], v147 offset:19456
	ds_read_b128 v[194:197], v147 offset:20480
	ds_read_b128 v[198:201], v147 offset:21504
	ds_read_b128 v[212:215], v147 offset:22528
	ds_read_b128 v[216:219], v147 offset:23552
	global_load_lds_dwordx4 v[202:203], off
	s_add_i32 m0, s13, 0x2000
	s_add_u32 vcc_lo, s52, 0x80000
	v_lshl_add_u64 v[220:221], s[52:53], 0, v[134:135]
	s_addc_u32 vcc_hi, s53, 0
	s_add_i32 s12, s12, s23
	global_load_lds_dwordx4 v[220:221], off
	v_lshl_add_u64 v[222:223], vcc, 0, v[130:131]
	s_mov_b32 m0, s12
	v_lshl_add_u64 v[224:225], s[14:15], 0, v[132:133]
	global_load_lds_dwordx4 v[222:223], off
	v_lshl_add_u64 v[222:223], vcc, 0, v[134:135]
	s_add_i32 m0, s12, 0x2000
	s_nop 0
	global_load_lds_dwordx4 v[222:223], off
	v_lshl_add_u64 v[222:223], s[14:15], 0, v[128:129]
	s_mov_b32 m0, s46
	s_nop 0
	global_load_lds_dwordx4 v[222:223], off
	s_mov_b32 m0, s54
	s_nop 0
	global_load_lds_dwordx4 v[224:225], off
	s_waitcnt vmcnt(8)
	s_waitcnt lgkmcnt(0)
	s_barrier
; #define PG8_STAGE(bufoff, gbase, voff) do { _Pragma("unroll") for (int _i = 0; _i < 2; ++_i) \
;         __builtin_amdgcn_global_load_lds((const unsigned*)((const char*)(gbase) + (voff)[_i]), (PG8_LAS unsigned*)(lds + (bufoff) + ldsw + _i * 8192), 16, 0, 0); } while (0)
; #define PG8_LDA(dst, b, h) do { _Pragma("unroll") for (int m = 0; m < 4; ++m) _Pragma("unroll") for (int k = 0; k < 2; ++k) dst[m][k] = *(const PG8_LAS bf16x8*)(lds + PG8_SA(b, h) + aoff + m * 2048 + k * 1024); } while (0)
; #define PG8_LDB(dst, b, h) do { _Pragma("unroll") for (int n = 0; n < 2; ++n) _Pragma("unroll") for (int k = 0; k < 2; ++k) dst[n][k] = *(const PG8_LAS bf16x8*)(lds + PG8_SB(b, h) + boff + n * 2048 + k * 1024); } while (0)
; #define PG8_MMA(ai, bj, At, Bt) do { __builtin_amdgcn_s_setprio(1); _Pragma("unroll") for (int m = 0; m < 4; ++m) _Pragma("unroll") for (int n = 0; n < 2; ++n) _Pragma("unroll") for (int k = 0; k < 2; ++k) \
;         acc[ai][bj][m][n] = __builtin_amdgcn_mfma_f32_16x16x32_bf16(Bt[n][k], At[m][k], acc[ai][bj][m][n], 0, 0, 0); __builtin_amdgcn_s_setprio(0); } while (0)
; #define PG8_WAIT_V(n) asm volatile("s_waitcnt vmcnt(" #n ")" ::: "memory")
; #define PG8_WAIT_L(n) asm volatile("s_waitcnt lgkmcnt(" #n ")" ::: "memory")
; #define PG8_BAR __builtin_amdgcn_s_barrier()
; #define PG8_SCHED __builtin_amdgcn_sched_barrier(0)
; template <class Epi, class Sched, bool ALIGN_EPI = false, bool SP2 = false>
; __device__ __forceinline__ void gemm_phase(PG8_LAS unsigned char* lds, const Gemm g, const Sched& S, const Epi& E, int tid_in) {
;     ...
;             PG8_WAIT_V(8); PG8_WAIT_L(0); PG8_BAR; PG8_MMA(1, 0, At, B0); PG8_MMA(1, 1, At, B1); PG8_BAR; PG8_SCHED;
;             PG8_LDB(B0, 1, 0); PG8_LDB(B1, 1, 1); PG8_SCHED; PG8_LDA(At, 1, 0); PG8_STAGE(PG8_SA(0, 1), a2 + hstep, voffA);
;             PG8_WAIT_V(8); PG8_WAIT_L(0); PG8_BAR; PG8_MMA(0, 0, At, B0); PG8_MMA(0, 1, At, B1); PG8_BAR; PG8_SCHED;
	s_setprio 1
	s_waitcnt lgkmcnt(0)
	v_mfma_f32_16x16x32_bf16 v[60:63], v[142:145], v[176:179], v[60:63]
	v_mfma_f32_16x16x32_bf16 v[56:59], v[152:155], v[176:179], v[56:59]
	v_mfma_f32_16x16x32_bf16 v[44:47], v[142:145], v[184:187], v[44:47]
	v_mfma_f32_16x16x32_bf16 v[40:43], v[152:155], v[184:187], v[40:43]
	v_mfma_f32_16x16x32_bf16 v[28:31], v[142:145], v[194:197], v[28:31]
	v_mfma_f32_16x16x32_bf16 v[24:27], v[152:155], v[194:197], v[24:27]
	v_mfma_f32_16x16x32_bf16 v[12:15], v[142:145], v[212:215], v[12:15]
	v_mfma_f32_16x16x32_bf16 v[8:11], v[152:155], v[212:215], v[8:11]
	v_mfma_f32_16x16x32_bf16 v[60:63], v[148:151], v[180:183], v[60:63]
	v_mfma_f32_16x16x32_bf16 v[56:59], v[156:159], v[180:183], v[56:59]
	v_mfma_f32_16x16x32_bf16 v[44:47], v[148:151], v[188:191], v[44:47]
	v_mfma_f32_16x16x32_bf16 v[40:43], v[156:159], v[188:191], v[40:43]
	v_mfma_f32_16x16x32_bf16 v[28:31], v[148:151], v[198:201], v[28:31]
	v_mfma_f32_16x16x32_bf16 v[24:27], v[156:159], v[198:201], v[24:27]
	v_mfma_f32_16x16x32_bf16 v[12:15], v[148:151], v[216:219], v[12:15]
	v_mfma_f32_16x16x32_bf16 v[8:11], v[156:159], v[216:219], v[8:11]
	s_setprio 0
	s_setprio 1
	v_mfma_f32_16x16x32_bf16 v[52:55], v[160:163], v[176:179], v[52:55]
	v_mfma_f32_16x16x32_bf16 v[48:51], v[168:171], v[176:179], v[48:51]
	v_mfma_f32_16x16x32_bf16 v[36:39], v[160:163], v[184:187], v[36:39]
	v_mfma_f32_16x16x32_bf16 v[32:35], v[168:171], v[184:187], v[32:35]
	v_mfma_f32_16x16x32_bf16 v[20:23], v[160:163], v[194:197], v[20:23]
	v_mfma_f32_16x16x32_bf16 v[16:19], v[168:171], v[194:197], v[16:19]
	v_mfma_f32_16x16x32_bf16 v[4:7], v[160:163], v[212:215], v[4:7]
	v_mfma_f32_16x16x32_bf16 v[0:3], v[168:171], v[212:215], v[0:3]
	v_mfma_f32_16x16x32_bf16 v[52:55], v[164:167], v[180:183], v[52:55]
	v_mfma_f32_16x16x32_bf16 v[48:51], v[172:175], v[180:183], v[48:51]
	v_mfma_f32_16x16x32_bf16 v[36:39], v[164:167], v[188:191], v[36:39]
	v_mfma_f32_16x16x32_bf16 v[32:35], v[172:175], v[188:191], v[32:35]
	v_mfma_f32_16x16x32_bf16 v[20:23], v[164:167], v[198:201], v[20:23]
	v_mfma_f32_16x16x32_bf16 v[16:19], v[172:175], v[198:201], v[16:19]
	v_mfma_f32_16x16x32_bf16 v[4:7], v[164:167], v[216:219], v[4:7]
	v_mfma_f32_16x16x32_bf16 v[0:3], v[172:175], v[216:219], v[0:3]
	s_setprio 0
	s_barrier
	s_add_i32 s12, 0, 0x18000
	s_add_i32 s13, 0, 0x1c000
	v_add_u32_e32 v156, s12, v146
	v_add_u32_e32 v172, s13, v146
	ds_read_b128 v[142:145], v156
	ds_read_b128 v[148:151], v156 offset:1024
	ds_read_b128 v[152:155], v156 offset:2048
	ds_read_b128 v[156:159], v156 offset:3072
	ds_read_b128 v[160:163], v172
	ds_read_b128 v[164:167], v172 offset:1024
	ds_read_b128 v[168:171], v172 offset:2048
	ds_read_b128 v[172:175], v172 offset:3072
	s_add_u32 s14, s14, 0x80000
	s_addc_u32 s15, s15, 0
	s_mov_b32 m0, s55
	v_lshl_add_u64 v[226:227], s[14:15], 0, v[128:129]
	ds_read_b128 v[176:179], v147 offset:32768
	ds_read_b128 v[180:183], v147 offset:33792
	ds_read_b128 v[184:187], v147 offset:34816
	ds_read_b128 v[188:191], v147 offset:35840
	ds_read_b128 v[194:197], v147 offset:36864
	ds_read_b128 v[198:201], v147 offset:37888
	ds_read_b128 v[212:215], v147 offset:38912
	ds_read_b128 v[216:219], v147 offset:39936
	global_load_lds_dwordx4 v[226:227], off
	v_lshl_add_u64 v[226:227], s[14:15], 0, v[132:133]
	s_mov_b32 m0, s56
	s_nop 0
	global_load_lds_dwordx4 v[226:227], off
	s_waitcnt vmcnt(8)
	s_waitcnt lgkmcnt(0)
	s_barrier
	s_setprio 1
	s_waitcnt lgkmcnt(0)
	v_mfma_f32_16x16x32_bf16 v[124:127], v[142:145], v[176:179], v[124:127]
	v_mfma_f32_16x16x32_bf16 v[120:123], v[152:155], v[176:179], v[120:123]
	v_mfma_f32_16x16x32_bf16 v[108:111], v[142:145], v[184:187], v[108:111]
	v_mfma_f32_16x16x32_bf16 v[104:107], v[152:155], v[184:187], v[104:107]
	v_mfma_f32_16x16x32_bf16 v[92:95], v[142:145], v[194:197], v[92:95]
	v_mfma_f32_16x16x32_bf16 v[88:91], v[152:155], v[194:197], v[88:91]
	v_mfma_f32_16x16x32_bf16 v[76:79], v[142:145], v[212:215], v[76:79]
	v_mfma_f32_16x16x32_bf16 v[72:75], v[152:155], v[212:215], v[72:75]
	v_mfma_f32_16x16x32_bf16 v[124:127], v[148:151], v[180:183], v[124:127]
	v_mfma_f32_16x16x32_bf16 v[120:123], v[156:159], v[180:183], v[120:123]
	v_mfma_f32_16x16x32_bf16 v[108:111], v[148:151], v[188:191], v[108:111]
	v_mfma_f32_16x16x32_bf16 v[104:107], v[156:159], v[188:191], v[104:107]
	v_mfma_f32_16x16x32_bf16 v[92:95], v[148:151], v[198:201], v[92:95]
	v_mfma_f32_16x16x32_bf16 v[88:91], v[156:159], v[198:201], v[88:91]
	v_mfma_f32_16x16x32_bf16 v[76:79], v[148:151], v[216:219], v[76:79]
	v_mfma_f32_16x16x32_bf16 v[72:75], v[156:159], v[216:219], v[72:75]
	s_setprio 0
	s_setprio 1
	v_mfma_f32_16x16x32_bf16 v[116:119], v[160:163], v[176:179], v[116:119]
	v_mfma_f32_16x16x32_bf16 v[112:115], v[168:171], v[176:179], v[112:115]
	v_mfma_f32_16x16x32_bf16 v[100:103], v[160:163], v[184:187], v[100:103]
	v_mfma_f32_16x16x32_bf16 v[96:99], v[168:171], v[184:187], v[96:99]
	v_mfma_f32_16x16x32_bf16 v[84:87], v[160:163], v[194:197], v[84:87]
	v_mfma_f32_16x16x32_bf16 v[80:83], v[168:171], v[194:197], v[80:83]
	v_mfma_f32_16x16x32_bf16 v[68:71], v[160:163], v[212:215], v[68:71]
	v_mfma_f32_16x16x32_bf16 v[64:67], v[168:171], v[212:215], v[64:67]
	v_mfma_f32_16x16x32_bf16 v[116:119], v[164:167], v[180:183], v[116:119]
	v_mfma_f32_16x16x32_bf16 v[112:115], v[172:175], v[180:183], v[112:115]
	v_mfma_f32_16x16x32_bf16 v[100:103], v[164:167], v[188:191], v[100:103]
	v_mfma_f32_16x16x32_bf16 v[96:99], v[172:175], v[188:191], v[96:99]
	v_mfma_f32_16x16x32_bf16 v[84:87], v[164:167], v[198:201], v[84:87]
	v_mfma_f32_16x16x32_bf16 v[80:83], v[172:175], v[198:201], v[80:83]
	v_mfma_f32_16x16x32_bf16 v[68:71], v[164:167], v[216:219], v[68:71]
	v_mfma_f32_16x16x32_bf16 v[64:67], v[172:175], v[216:219], v[64:67]
	s_setprio 0
	s_barrier
; __device__ __forceinline__ float rstd_of(float ss, float inv_n) { return __builtin_amdgcn_rsqf(ss * inv_n + RMS_EPS); }
; #define PG8_STAGE(bufoff, gbase, voff) do { _Pragma("unroll") for (int _i = 0; _i < 2; ++_i) \
;         __builtin_amdgcn_global_load_lds((const unsigned*)((const char*)(gbase) + (voff)[_i]), (PG8_LAS unsigned*)(lds + (bufoff) + ldsw + _i * 8192), 16, 0, 0); } while (0)
; #define PG8_LDA(dst, b, h) do { _Pragma("unroll") for (int m = 0; m < 4; ++m) _Pragma("unroll") for (int k = 0; k < 2; ++k) dst[m][k] = *(const PG8_LAS bf16x8*)(lds + PG8_SA(b, h) + aoff + m * 2048 + k * 1024); } while (0)
; #define PG8_WAIT_V(n) asm volatile("s_waitcnt vmcnt(" #n ")" ::: "memory")
; #define PG8_WAIT_L(n) asm volatile("s_waitcnt lgkmcnt(" #n ")" ::: "memory")
; #define PG8_BAR __builtin_amdgcn_s_barrier()
; #define PG8_SCHED __builtin_amdgcn_sched_barrier(0)
;     __device__ __forceinline__ void operator()(const f32x4 (&acc)[2][2][4][2], const Unit& u, int wr, int wc, int fr, int fq) const {
;         const int seg = u.pn >> 2; const int colt = (u.pn & 3) * BM + wc * 32 + 8 * fq;
;         const int row0 = u.pm * BM + wr * 64 + fr;
;         const float qs = (seg == 2) ? 0.125f : 1.0f;
;         bf16_t* op = base + (size_t)seg * ((size_t)16384 * 1024) + (size_t)row0 * 1024 + colt;
;         float rsv[2][4];
; #pragma unroll
;         for (int ai = 0; ai < 2; ++ai)
; #pragma unroll
;             for (int m = 0; m < 4; ++m) rsv[ai][m] = gld<float>(ss + row0 + ai * HALF + m * 16);
;         __builtin_amdgcn_sched_barrier(0);
;         const int kb_b = (u.pm * BM) >> 11, kb_s0 = row0 & 2047;
; #pragma unroll
;         for (int ai = 0; ai < 2; ++ai)
; #pragma unroll
;             for (int m = 0; m < 4; ++m) {
;                 const float rs = rstd_of(rsv[ai][m], 1.0f / 2048.0f) * qs;
; template <class Epi, class Sched, bool ALIGN_EPI = false, bool SP2 = false>
; __device__ __forceinline__ void gemm_phase(PG8_LAS unsigned char* lds, const Gemm g, const Sched& S, const Epi& E, int tid_in) {
;     ...
;             PG8_LDA(At, 1, 1); PG8_STAGE(PG8_SB(1, 0), b3, voffB); PG8_STAGE(PG8_SB(1, 1), b3 + hstep, voffB); PG8_STAGE(PG8_SA(1, 0), a3, voffA);
;             PG8_WAIT_V(8); PG8_WAIT_L(0); PG8_BAR; PG8_MMA(1, 0, At, B0); PG8_MMA(1, 1, At, B1); PG8_BAR; PG8_SCHED;
	s_add_i32 s12, s12, s23
	v_lshl_add_u64 v[202:203], v[202:203], 0, s[4:5]
	s_mov_b32 m0, s12
	ds_read_b128 v[176:179], v147 offset:49152
	ds_read_b128 v[180:183], v147 offset:50176
	ds_read_b128 v[184:187], v147 offset:51200
	ds_read_b128 v[188:191], v147 offset:52224
	ds_read_b128 v[194:197], v147 offset:53248
	ds_read_b128 v[198:201], v147 offset:54272
	ds_read_b128 v[212:215], v147 offset:55296
	ds_read_b128 v[216:219], v147 offset:56320
	global_load_lds_dwordx4 v[202:203], off
	s_add_i32 m0, s12, 0x2000
	s_add_u32 s14, s52, 0x80080
	v_lshl_add_u64 v[202:203], v[220:221], 0, s[4:5]
	s_addc_u32 s15, s53, 0
	s_add_i32 s12, s13, s23
	global_load_lds_dwordx4 v[202:203], off
	v_lshl_add_u64 v[202:203], s[14:15], 0, v[130:131]
	s_mov_b32 m0, s12
	s_nop 0
	global_load_lds_dwordx4 v[202:203], off
	v_lshl_add_u64 v[202:203], s[14:15], 0, v[134:135]
	s_add_i32 m0, s12, 0x2000
	s_nop 0
	global_load_lds_dwordx4 v[202:203], off
	v_lshl_add_u64 v[202:203], v[222:223], 0, s[4:5]
	s_mov_b32 m0, s85
	s_nop 0
	global_load_lds_dwordx4 v[202:203], off
	v_lshl_add_u64 v[202:203], v[224:225], 0, s[4:5]
	s_mov_b32 m0, s86
	s_nop 0
	global_load_lds_dwordx4 v[202:203], off
	s_waitcnt vmcnt(8)
	s_waitcnt lgkmcnt(0)
	s_barrier
	s_setprio 1
	s_waitcnt lgkmcnt(0)
	v_mfma_f32_16x16x32_bf16 v[60:63], v[142:145], v[176:179], v[60:63]
	v_mfma_f32_16x16x32_bf16 v[56:59], v[152:155], v[176:179], v[56:59]
	v_mfma_f32_16x16x32_bf16 v[44:47], v[142:145], v[184:187], v[44:47]
	v_mfma_f32_16x16x32_bf16 v[40:43], v[152:155], v[184:187], v[40:43]
	v_mfma_f32_16x16x32_bf16 v[28:31], v[142:145], v[194:197], v[28:31]
	v_mfma_f32_16x16x32_bf16 v[24:27], v[152:155], v[194:197], v[24:27]
	v_mfma_f32_16x16x32_bf16 v[12:15], v[142:145], v[212:215], v[12:15]
	v_mfma_f32_16x16x32_bf16 v[8:11], v[152:155], v[212:215], v[8:11]
	v_mfma_f32_16x16x32_bf16 v[60:63], v[148:151], v[180:183], v[60:63]
	v_mfma_f32_16x16x32_bf16 v[56:59], v[156:159], v[180:183], v[56:59]
	v_mfma_f32_16x16x32_bf16 v[44:47], v[148:151], v[188:191], v[44:47]
	v_mfma_f32_16x16x32_bf16 v[40:43], v[156:159], v[188:191], v[40:43]
	v_mfma_f32_16x16x32_bf16 v[28:31], v[148:151], v[198:201], v[28:31]
	v_mfma_f32_16x16x32_bf16 v[24:27], v[156:159], v[198:201], v[24:27]
	v_mfma_f32_16x16x32_bf16 v[12:15], v[148:151], v[216:219], v[12:15]
	v_mfma_f32_16x16x32_bf16 v[8:11], v[156:159], v[216:219], v[8:11]
	s_setprio 0
	s_setprio 1
	v_mfma_f32_16x16x32_bf16 v[52:55], v[160:163], v[176:179], v[52:55]
	v_mfma_f32_16x16x32_bf16 v[48:51], v[168:171], v[176:179], v[48:51]
	v_mfma_f32_16x16x32_bf16 v[36:39], v[160:163], v[184:187], v[36:39]
	v_mfma_f32_16x16x32_bf16 v[32:35], v[168:171], v[184:187], v[32:35]
	v_mfma_f32_16x16x32_bf16 v[20:23], v[160:163], v[194:197], v[20:23]
	v_mfma_f32_16x16x32_bf16 v[16:19], v[168:171], v[194:197], v[16:19]
	v_mfma_f32_16x16x32_bf16 v[4:7], v[160:163], v[212:215], v[4:7]
	v_mfma_f32_16x16x32_bf16 v[0:3], v[168:171], v[212:215], v[0:3]
	v_mfma_f32_16x16x32_bf16 v[52:55], v[164:167], v[180:183], v[52:55]
	v_mfma_f32_16x16x32_bf16 v[48:51], v[172:175], v[180:183], v[48:51]
	v_mfma_f32_16x16x32_bf16 v[36:39], v[164:167], v[188:191], v[36:39]
	v_mfma_f32_16x16x32_bf16 v[32:35], v[172:175], v[188:191], v[32:35]
	v_mfma_f32_16x16x32_bf16 v[20:23], v[164:167], v[198:201], v[20:23]
	v_mfma_f32_16x16x32_bf16 v[16:19], v[172:175], v[198:201], v[16:19]
	v_mfma_f32_16x16x32_bf16 v[4:7], v[164:167], v[216:219], v[4:7]
	v_mfma_f32_16x16x32_bf16 v[0:3], v[172:175], v[216:219], v[0:3]
	s_setprio 0
	s_barrier
	s_add_i32 s97, s97, 2
	s_add_u32 s37, s37, 0x100
	s_addc_u32 s41, s41, 0
	s_add_u32 s50, s50, 0x100
	s_addc_u32 s51, s51, 0
	s_cmp_gt_u32 s97, 29
	s_cbranch_scc0 .LBB0_85
	s_and_b64 vcc, exec, s[30:31]
	s_cbranch_vccz .LBB0_88
	s_barrier
.LBB0_88:
	v_lshl_add_u32 v144, s40, 8, v137
	v_ashrrev_i32_e32 v145, 31, v144
	s_ashr_i32 s14, s2, 2
	s_lshl_b32 s2, s2, 8
	s_and_b32 s2, s2, 0x300
	s_or_b32 s10, s2, s57
	s_cmp_eq_u32 s14, 2
	s_cselect_b64 vcc, -1, 0
	s_ashr_i32 s15, s14, 31
	s_lshl_b64 s[2:3], s[14:15], 25
	s_add_u32 s2, s24, s2
	v_or_b32_e32 v148, s10, v136
	v_lshlrev_b64 v[142:143], 11, v[144:145]
	s_addc_u32 s3, s25, s3
	v_lshl_add_u64 v[142:143], s[2:3], 0, v[142:143]
	v_lshlrev_b32_e32 v192, 1, v148
	v_cndmask_b32_e32 v150, 1.0, v248, vcc
	v_lshl_add_u64 v[142:143], v[142:143], 0, v[192:193]
	v_and_b32_e32 v148, 0x7cf, v144
	s_waitcnt vmcnt(16)
	v_mov_b32_e32 v154, v228
	v_mov_b32_e32 v157, v229
	v_mov_b32_e32 v156, v230
	v_mov_b32_e32 v155, v231
	v_mov_b32_e32 v153, v232
	v_mov_b32_e32 v152, v233
	v_mov_b32_e32 v151, v234
	v_mov_b32_e32 v149, v244
	v_fmamk_f32 v144, v154, 0x3a000000, v246
	v_rsq_f32_e32 v144, v144
	s_cmp_lg_u32 s14, 3
	s_cselect_b64 s[2:3], -1, 0
	s_lshl_b32 s11, s40, 1
	v_mul_f32_e32 v144, v150, v144
	v_or_b32_e32 v154, s87, v148
	v_pk_mul_f32 v[126:127], v[126:127], v[144:145] op_sel_hi:[1,0]
	v_pk_mul_f32 v[124:125], v[124:125], v[144:145] op_sel_hi:[1,0]
	s_and_b32 s11, s11, -16
	v_pk_mul_f32 v[158:159], v[122:123], v[144:145] op_sel_hi:[1,0]
	v_pk_mul_f32 v[122:123], v[120:121], v[144:145] op_sel_hi:[1,0]
	v_cvt_pk_bf16_f32 v120, v124, v125
	v_cvt_pk_bf16_f32 v121, v126, v127
	s_and_b64 vcc, exec, s[2:3]
	v_lshlrev_b32_e32 v192, 6, v154
	v_lshlrev_b32_e32 v124, 1, v136
	v_mov_b64_e32 v[126:127], v[142:143]
	v_cvt_pk_bf16_f32 v122, v122, v123
	v_cvt_pk_bf16_f32 v123, v158, v159
	s_cbranch_vccnz .LBB0_90
	s_lshr_b32 s12, s10, 6
	s_or_b32 s14, s12, s11
	s_ashr_i32 s15, s14, 31
	s_lshl_b64 s[14:15], s[14:15], 18
	s_add_u32 s14, s88, s14
	s_addc_u32 s15, s89, s15
	v_lshl_add_u64 v[126:127], s[14:15], 0, v[192:193]
	v_mov_b32_e32 v125, v193
	v_lshl_add_u64 v[126:127], v[126:127], 0, v[124:125]
